# attention key loops: the fourth score accumulator is initialised by taking the broadcast -max vector as the MFMA SrcC directly (8 v_mov_b64 and an s_nop per key step removed)
# speedup vs baseline: 1.0108x; 1.0018x over previous
; #define LAS __attribute__((address_space(3)))
; #define AT_LOAD(t) do { const GAS u32x4* Kg_ = (const GAS u32x4*)(Kp + (size_t)(t) * 128 * DK); const GAS u32x4* Vg_ = (const GAS u32x4*)(Vp + (size_t)(t) * 128 * 64); \
;         _Pragma("unroll") for (int i_ = 0; i_ < NKC; ++i_) kreg[i_] = Kg_[tid + 512 * i_]; vreg[0] = Vg_[tid]; vreg[1] = Vg_[tid + 512]; } while (0)
; #define AT_STORE(bf_) do { LAS unsigned char* nb_ = lds + (bf_) * AT_KBUF; _Pragma("unroll") for (int i_ = 0; i_ < NKC; ++i_) *(LAS u32x4*)(nb_ + koff[i_]) = kreg[i_]; \
;         *(LAS u32x4*)(lds + (bf_) * AT_VBUF + voff[0]) = vreg[0]; *(LAS u32x4*)(lds + (bf_) * AT_VBUF + voff[1]) = vreg[1]; } while (0)
; template <int DK>
; __device__ __forceinline__ void attn_unit(LAS unsigned char* lds, const GAS bf16* Qp, const GAS bf16* Kp, const GAS bf16* Vp, GAS bf16* Yp, int b, int j, int nkeys, int tid, int lane, int wave) {
;     ...
;         { LAS unsigned char* kb = lds + cur * AT_KBUF + kfo;
;           bf16x8 ka[2][4];
; #pragma unroll
;           for (int q4 = 0; q4 < 4; ++q4) ka[0][q4] = *(LAS bf16x8*)(kb + q4 * 32 * KSTR);
; #pragma unroll
;           for (int d0 = 0; d0 < ND; ++d0) {
;               if (d0 + 1 < ND) {
; #pragma unroll
;                   for (int q4 = 0; q4 < 4; ++q4) ka[(d0 + 1) & 1][q4] = *(LAS bf16x8*)(kb + q4 * 32 * KSTR + (d0 + 1) * 32);
;               }
; #pragma unroll
;               for (int q4 = 0; q4 < 4; ++q4) p[q4] = __builtin_amdgcn_mfma_f32_32x32x16_bf16(ka[d0 & 1][q4], qr[d0], d0 == 0 ? negm : p[q4], 0, 0, 0);
;               if (d0 == 0) { if (t + 1 < NT) AT_STORE(cur ^ 1); if (t + 2 < NT) AT_LOAD(t + 2); }
.LBB0_137:
	s_add_i32 s11, s10, -2
	s_and_b32 s11, s11, 1
	s_mul_i32 s12, s11, 0x6800
	v_add_u32_e32 v0, s12, v237
	ds_read_b128 v[6:9], v0
	ds_read_b128 v[2:5], v0 offset:32
	s_add_i32 s12, s10, -1
	s_cmp_ge_u32 s12, s8
	s_waitcnt lgkmcnt(1)
	v_mfma_f32_32x32x16_bf16 v[128:143], v[6:9], v[144:147], v[64:79]
	ds_read_b128 v[10:13], v0 offset:6656
	ds_read_b128 v[6:9], v0 offset:6688
	s_waitcnt lgkmcnt(1)
	v_mfma_f32_32x32x16_bf16 v[112:127], v[10:13], v[144:147], v[64:79]
	ds_read_b128 v[80:83], v0 offset:13312
	ds_read_b128 v[10:13], v0 offset:13344
	ds_read_b128 v[214:217], v0 offset:19968
	ds_read_b128 v[188:191], v0 offset:20000
	s_waitcnt lgkmcnt(3)
	v_mfma_f32_32x32x16_bf16 v[96:111], v[80:83], v[144:147], v[64:79]
	s_waitcnt lgkmcnt(1)
	v_mfma_f32_32x32x16_bf16 v[80:95], v[214:217], v[144:147], v[64:79]
	s_cbranch_scc1 .LBB0_139
	s_xor_b32 s12, s11, 1
	s_lshl_b32 s13, s12, 14
	s_add_i32 s13, s13, 0
	s_mulk_i32 s12, 0x2800
	v_add_u32_e32 v14, s13, v235
	s_add_i32 s13, s13, s12
	v_add_u32_e32 v15, s13, v232
	s_waitcnt vmcnt(6)
	ds_write_b128 v15, v[160:163]
	v_add_u32_e32 v15, s13, v233
	s_waitcnt vmcnt(5)
	ds_write_b128 v15, v[164:167]
	v_add_u32_e32 v15, s13, v234
	s_waitcnt vmcnt(4)
	ds_write_b128 v15, v[176:179]
	s_waitcnt vmcnt(3)
	ds_write_b128 v14, v[180:183] offset:53248
	s_waitcnt vmcnt(2)
	ds_write_b128 v14, v[184:187] offset:57344

; #define LAS __attribute__((address_space(3)))
; #define AT_LOAD(t) do { const GAS u32x4* Kg_ = (const GAS u32x4*)(Kp + (size_t)(t) * 128 * DK); const GAS u32x4* Vg_ = (const GAS u32x4*)(Vp + (size_t)(t) * 128 * 64); \
;         _Pragma("unroll") for (int i_ = 0; i_ < NKC; ++i_) kreg[i_] = Kg_[tid + 512 * i_]; vreg[0] = Vg_[tid]; vreg[1] = Vg_[tid + 512]; } while (0)
; #define AT_STORE(bf_) do { LAS unsigned char* nb_ = lds + (bf_) * AT_KBUF; _Pragma("unroll") for (int i_ = 0; i_ < NKC; ++i_) *(LAS u32x4*)(nb_ + koff[i_]) = kreg[i_]; \
;         *(LAS u32x4*)(lds + (bf_) * AT_VBUF + voff[0]) = vreg[0]; *(LAS u32x4*)(lds + (bf_) * AT_VBUF + voff[1]) = vreg[1]; } while (0)
; template <int DK>
; __device__ __forceinline__ void attn_unit(LAS unsigned char* lds, const GAS bf16* Qp, const GAS bf16* Kp, const GAS bf16* Vp, GAS bf16* Yp, int b, int j, int nkeys, int tid, int lane, int wave) {
;     ...
;         { LAS unsigned char* kb = lds + cur * AT_KBUF + kfo;
;           bf16x8 ka[2][4];
; #pragma unroll
;           for (int q4 = 0; q4 < 4; ++q4) ka[0][q4] = *(LAS bf16x8*)(kb + q4 * 32 * KSTR);
; #pragma unroll
;           for (int d0 = 0; d0 < ND; ++d0) {
;               if (d0 + 1 < ND) {
; #pragma unroll
;                   for (int q4 = 0; q4 < 4; ++q4) ka[(d0 + 1) & 1][q4] = *(LAS bf16x8*)(kb + q4 * 32 * KSTR + (d0 + 1) * 32);
;               }
; #pragma unroll
;               for (int q4 = 0; q4 < 4; ++q4) p[q4] = __builtin_amdgcn_mfma_f32_32x32x16_bf16(ka[d0 & 1][q4], qr[d0], d0 == 0 ? negm : p[q4], 0, 0, 0);
;               if (d0 == 0) { if (t + 1 < NT) AT_STORE(cur ^ 1); if (t + 2 < NT) AT_LOAD(t + 2); }
.LBB0_159:
	s_add_i32 s8, s7, -2
	s_and_b32 s8, s8, 1
	s_mul_i32 s9, s8, 0x6800
	v_add_u32_e32 v0, s9, v242
	ds_read_b128 v[66:69], v0
	ds_read_b128 v[162:165], v0 offset:32
	s_add_i32 s9, s7, -1
	s_cmp_ge_u32 s9, s4
	s_waitcnt lgkmcnt(1)
	v_mfma_f32_32x32x16_bf16 v[114:129], v[66:69], v[130:133], v[50:65]
	ds_read_b128 v[66:69], v0 offset:4608
	ds_read_b128 v[166:169], v0 offset:4640
	s_waitcnt lgkmcnt(1)
	v_mfma_f32_32x32x16_bf16 v[98:113], v[66:69], v[130:133], v[50:65]
	ds_read_b128 v[66:69], v0 offset:9216
	ds_read_b128 v[170:173], v0 offset:9248
	ds_read_b128 v[186:189], v0 offset:13824
	ds_read_b128 v[174:177], v0 offset:13856
	s_waitcnt lgkmcnt(3)
	v_mfma_f32_32x32x16_bf16 v[82:97], v[66:69], v[130:133], v[50:65]
	s_waitcnt lgkmcnt(1)
	v_mfma_f32_32x32x16_bf16 v[66:81], v[186:189], v[130:133], v[50:65]
	s_cbranch_scc1 .LBB0_161
	s_xor_b32 s9, s8, 1
	s_lshl_b32 s10, s9, 14
	s_add_i32 s10, s10, 0
	s_mulk_i32 s9, 0x2800
	v_add_u32_e32 v186, s10, v235
	s_add_i32 s10, s10, s9
	v_add_u32_e32 v187, s10, v240
	s_waitcnt vmcnt(3)
	ds_write_b128 v187, v[146:149]
	v_add_u32_e32 v187, s10, v241
	s_waitcnt vmcnt(2)
	ds_write_b128 v187, v[150:153]
	s_waitcnt vmcnt(1)
	ds_write_b128 v186, v[154:157] offset:53248
	s_waitcnt vmcnt(0)
	ds_write_b128 v186, v[158:161] offset:57344
